# scan pass 1 cumulative-decay stage: row reads batched (one LDS wait per loop trip, own rows read together with exec-masked adds)
# speedup vs baseline: 1.0146x; 1.0146x over previous
; #define LAS __attribute__((address_space(3)))
; __device__ __forceinline__ void scan_pass1(const ScanP& sp, int b, int h, int seg, LAS unsigned char* lds) {
;     ...
;             for (int s4 = 0; s4 < w; ++s4) {
;                 const LAS float* lp_ = lwS + (4 * s4) * 64 + j4;
;                 const f32x4 x0 = *(const LAS f32x4*)lp_, x1 = *(const LAS f32x4*)(lp_ + 64), x2 = *(const LAS f32x4*)(lp_ + 128), x3 = *(const LAS f32x4*)(lp_ + 192);
;                 cl += (x0 + x1) + (x2 + x3);
;             }
.LBB0_256:
	ds_read_b128 v[104:107], v0
	ds_read_b128 v[110:113], v0 offset:256
	ds_read_b128 v[114:117], v0 offset:512
	ds_read_b128 v[150:153], v0 offset:768
	ds_read_b128 v[230:233], v0 offset:1024
	ds_read_b128 v[234:237], v0 offset:1280
	ds_read_b128 v[238:241], v0 offset:1536
	ds_read_b128 v[242:245], v0 offset:1792
	s_add_i32 s0, s0, 2
	s_cmp_eq_u32 s64, s0
	v_add_u32_e32 v0, 0x800, v0
	s_waitcnt lgkmcnt(4)
	v_pk_add_f32 v[2:3], v[106:107], v[112:113]
	v_pk_add_f32 v[104:105], v[104:105], v[110:111]
	v_pk_add_f32 v[106:107], v[116:117], v[152:153]
	v_pk_add_f32 v[110:111], v[114:115], v[150:151]
	v_pk_add_f32 v[2:3], v[2:3], v[106:107]
	v_pk_add_f32 v[104:105], v[104:105], v[110:111]
	v_pk_add_f32 v[2:3], v[82:83], v[2:3]
	v_pk_add_f32 v[118:119], v[80:81], v[104:105]
	s_waitcnt lgkmcnt(0)
	v_pk_add_f32 v[82:83], v[232:233], v[236:237]
	v_pk_add_f32 v[80:81], v[230:231], v[234:235]
	v_pk_add_f32 v[104:105], v[240:241], v[244:245]
	v_pk_add_f32 v[106:107], v[238:239], v[242:243]
	v_pk_add_f32 v[82:83], v[82:83], v[104:105]
	v_pk_add_f32 v[80:81], v[80:81], v[106:107]
	v_pk_add_f32 v[82:83], v[2:3], v[82:83]
	v_pk_add_f32 v[80:81], v[118:119], v[80:81]
	s_cbranch_scc0 .LBB0_256
	s_lshl_b32 s0, s64, 10
	s_andn2_b64 vcc, exec, s[2:3]
	s_cbranch_vccz .LBB0_260
	s_branch .LBB0_261

; #define LAS __attribute__((address_space(3)))
; __device__ __forceinline__ void scan_pass1(const ScanP& sp, int b, int h, int seg, LAS unsigned char* lds) {
;     ...
;             for (int q = 0; q < 4; ++q) { const int s = 4 * w + q; const f32x4 x = *(const LAS f32x4*)(lwS + s * 64 + j4); if (s <= tt) cl += x; }
.LBB0_261:
	v_add_u32_e32 v0, s92, v162
	v_add_u32_e32 v246, s81, v162
	v_add_u32_e32 v247, s20, v162
	ds_read_b128 v[104:107], v0 offset:24576
	ds_read_b128 v[230:233], v0 offset:24832
	ds_read_b128 v[234:237], v246 offset:24576
	ds_read_b128 v[238:241], v247 offset:24576
	s_mov_b64 s[0:1], exec
	s_waitcnt lgkmcnt(0)
	s_and_b64 exec, s[0:1], s[12:13]
	v_pk_add_f32 v[82:83], v[82:83], v[106:107]
	v_pk_add_f32 v[80:81], v[80:81], v[104:105]
	s_and_b64 exec, s[0:1], s[14:15]
	v_pk_add_f32 v[82:83], v[82:83], v[232:233]
	v_pk_add_f32 v[80:81], v[80:81], v[230:231]
	s_and_b64 exec, s[0:1], s[16:17]
	v_pk_add_f32 v[82:83], v[82:83], v[236:237]
	v_pk_add_f32 v[80:81], v[80:81], v[234:235]
	s_and_b64 exec, s[0:1], s[18:19]
	v_pk_add_f32 v[82:83], v[82:83], v[240:241]
	v_pk_add_f32 v[80:81], v[80:81], v[238:239]

; #define LAS __attribute__((address_space(3)))
; #define MFMA32(a, b, c) __builtin_amdgcn_mfma_f32_32x32x16_bf16((a), (b), (c), 0, 0, 0)
; __device__ __forceinline__ void scan_pass1(const ScanP& sp, int b, int h, int seg, LAS unsigned char* lds) {
;     ...
;             if (isH) {
; #pragma unroll
;                 for (int ks = 0; ks < 2; ++ks) vfr[ks] = *(const LAS bf16x8*)(lds + O_VT + (icol * 40 + ks * 16 + hh * 8) * 2);
; #pragma unroll
;                 for (int ks = 0; ks < 2; ++ks) {
;                     P1 = MFMA32(*(const LAS bf16x8*)(lds + O_MK + (ln * 40 + ks * 16 + hh * 8) * 2), vfr[ks], P1);
;                     P2 = MFMA32(*(const LAS bf16x8*)(lds + O_NK + (ln * 40 + ks * 16 + hh * 8) * 2), vfr[ks], P2);
;                 }
.LBB0_304:
	s_andn2_b64 vcc, exec, s[0:1]
	v_or_b32_e32 v121, s82, v189
	s_cbranch_vccnz .LBB0_309
	v_mul_u32_u24_e32 v68, 0x50, v121
	s_movk_i32 s0, 0x50
	v_add3_u32 v68, 0, v113, v68
	v_mad_u32_u24 v72, v189, s0, v113
	s_add_i32 s0, 0, 0x10400
	ds_read_b128 v[92:95], v68 offset:61440
	ds_read_b128 v[96:99], v68 offset:61472
	v_add_u32_e32 v68, s0, v72
	ds_read_b128 v[68:71], v68
	s_add_i32 s1, 0, 0x10e00
	s_waitcnt lgkmcnt(0)
	v_mfma_f32_32x32x16_bf16 v[36:51], v[68:71], v[92:95], v[36:51]
	v_add_u32_e32 v68, s1, v72
	ds_read_b128 v[68:71], v68
	v_add_u32_e32 v72, 32, v72
	s_waitcnt lgkmcnt(0)
	v_mfma_f32_32x32x16_bf16 v[52:67], v[68:71], v[92:95], v[52:67]
	v_add_u32_e32 v68, s0, v72
	ds_read_b128 v[68:71], v68
	s_waitcnt lgkmcnt(0)
	v_mfma_f32_32x32x16_bf16 v[36:51], v[68:71], v[96:99], v[36:51]
	v_add_u32_e32 v68, s1, v72
	ds_read_b128 v[68:71], v68
	s_waitcnt lgkmcnt(0)
	v_mfma_f32_32x32x16_bf16 v[52:67], v[68:71], v[96:99], v[52:67]
	s_branch .LBB0_310
.LBB0_309:
	v_mov_b32_e32 v113, v69
	v_mov_b32_e32 v112, v68
